# hand-written blocked lru_fix carry fold (16-byte loads, per-wave segment, batched prefix)
# speedup vs baseline: 1.1044x; 1.0018x over previous
; __device__ __forceinline__ void lru_fix_phase(const Params& p, const XcdBarrier& xb) {
;     ...
;   const bool blocked = (gridDim.x == 256);
;   for (int k = 0; k < (blocked ? 1 : 0); k++) {
;     const int li0 = blockIdx.x * 4;
;     const int b = li0 >> 7, s0 = li0 & 127;
;     const float* sg = SEG + (size_t)(b * 128) * 1024 + ch;
;     float carry = 0.f;
; #pragma unroll 8
;     for (int q = 0; q < s0; q++) carry = sg[(size_t)q * 1024] * carry + sg[(size_t)q * 1024 + 512];
.LBB0_1756:
	s_cmpk_lg_i32 s42, 0x100
	s_mov_b32 s0, 0
	s_cbranch_scc1 .LBB0_1776
	v_and_b32_e32 v136, 63, v128
	v_lshrrev_b32_e32 v137, 6, v128
	v_readlane_b32 s7, v254, 0
	v_readfirstlane_b32 s6, v137
	s_nop 3
	s_lshl_b32 s7, s7, 2
	s_lshr_b32 s14, s7, 7
	s_and_b32 s15, s7, 0x7f
	s_and_b32 s16, s6, 1
	s_lshr_b32 s17, s6, 1
	s_add_u32 s18, s15, s17
	s_lshl_b32 s19, s16, 8
	v_lshl_add_u32 v136, v136, 2, s19
	v_lshlrev_b32_e32 v129, 2, v136
	v_lshlrev_b32_e32 v130, 1, v136
	v_mov_b32_e32 v132, 0
	v_mov_b32_e32 v133, 0
	v_mov_b32_e32 v134, 0
	v_mov_b32_e32 v135, 0
	s_lshl_b32 s19, s14, 19
	s_add_u32 s8, s96, 0xf508100
	s_addc_u32 s9, s97, 0
	s_add_u32 s8, s8, s19
	s_addc_u32 s9, s9, 0
	s_mov_b32 s10, 0
.Llf_pre:
	s_cmp_ge_u32 s10, s18
	s_cbranch_scc1 .Llf_pre_done
	s_lshl_b32 s11, s10, 12
	s_add_u32 s12, s8, s11
	s_addc_u32 s13, s9, 0
	global_load_dwordx4 v[0:3], v129, s[12:13]
	global_load_dwordx4 v[4:7], v129, s[12:13] offset:2048
	s_add_u32 s12, s12, 0x1000
	s_addc_u32 s13, s13, 0
	global_load_dwordx4 v[8:11], v129, s[12:13]
	global_load_dwordx4 v[12:15], v129, s[12:13] offset:2048
	s_add_u32 s12, s12, 0x1000
	s_addc_u32 s13, s13, 0
	global_load_dwordx4 v[16:19], v129, s[12:13]
	global_load_dwordx4 v[20:23], v129, s[12:13] offset:2048
	s_add_u32 s12, s12, 0x1000
	s_addc_u32 s13, s13, 0
	global_load_dwordx4 v[24:27], v129, s[12:13]
	global_load_dwordx4 v[28:31], v129, s[12:13] offset:2048
	s_add_u32 s12, s12, 0x1000
	s_addc_u32 s13, s13, 0
	global_load_dwordx4 v[32:35], v129, s[12:13]
	global_load_dwordx4 v[36:39], v129, s[12:13] offset:2048
	s_add_u32 s12, s12, 0x1000
	s_addc_u32 s13, s13, 0
	global_load_dwordx4 v[40:43], v129, s[12:13]
	global_load_dwordx4 v[44:47], v129, s[12:13] offset:2048
	s_add_u32 s12, s12, 0x1000
	s_addc_u32 s13, s13, 0
	global_load_dwordx4 v[48:51], v129, s[12:13]
	global_load_dwordx4 v[52:55], v129, s[12:13] offset:2048
	s_add_u32 s12, s12, 0x1000
	s_addc_u32 s13, s13, 0
	global_load_dwordx4 v[56:59], v129, s[12:13]
	global_load_dwordx4 v[60:63], v129, s[12:13] offset:2048
	s_add_u32 s12, s12, 0x1000
	s_addc_u32 s13, s13, 0
	global_load_dwordx4 v[64:67], v129, s[12:13]
	global_load_dwordx4 v[68:71], v129, s[12:13] offset:2048
	s_add_u32 s12, s12, 0x1000
	s_addc_u32 s13, s13, 0
	global_load_dwordx4 v[72:75], v129, s[12:13]
	global_load_dwordx4 v[76:79], v129, s[12:13] offset:2048
	s_add_u32 s12, s12, 0x1000
	s_addc_u32 s13, s13, 0
	global_load_dwordx4 v[80:83], v129, s[12:13]
	global_load_dwordx4 v[84:87], v129, s[12:13] offset:2048
	s_add_u32 s12, s12, 0x1000
	s_addc_u32 s13, s13, 0
	global_load_dwordx4 v[88:91], v129, s[12:13]
	global_load_dwordx4 v[92:95], v129, s[12:13] offset:2048
	s_add_u32 s12, s12, 0x1000
	s_addc_u32 s13, s13, 0
	global_load_dwordx4 v[96:99], v129, s[12:13]
	global_load_dwordx4 v[100:103], v129, s[12:13] offset:2048
	s_add_u32 s12, s12, 0x1000
	s_addc_u32 s13, s13, 0
	global_load_dwordx4 v[104:107], v129, s[12:13]
	global_load_dwordx4 v[108:111], v129, s[12:13] offset:2048
	s_add_u32 s12, s12, 0x1000
	s_addc_u32 s13, s13, 0
	global_load_dwordx4 v[112:115], v129, s[12:13]
	global_load_dwordx4 v[116:119], v129, s[12:13] offset:2048
	s_add_u32 s12, s12, 0x1000
	s_addc_u32 s13, s13, 0
	global_load_dwordx4 v[120:123], v129, s[12:13]
	global_load_dwordx4 v[124:127], v129, s[12:13] offset:2048
	s_sub_u32 s11, s18, s10
	s_waitcnt vmcnt(0)
	s_cmp_le_u32 s11, 0
	s_cbranch_scc1 .Llf_pre_done
	v_fma_f32 v132, v0, v132, v4
	v_fma_f32 v133, v1, v133, v5
	v_fma_f32 v134, v2, v134, v6
	v_fma_f32 v135, v3, v135, v7
	s_cmp_le_u32 s11, 1
	s_cbranch_scc1 .Llf_pre_done
	v_fma_f32 v132, v8, v132, v12
	v_fma_f32 v133, v9, v133, v13
	v_fma_f32 v134, v10, v134, v14
	v_fma_f32 v135, v11, v135, v15
	s_cmp_le_u32 s11, 2
	s_cbranch_scc1 .Llf_pre_done
	v_fma_f32 v132, v16, v132, v20
	v_fma_f32 v133, v17, v133, v21
	v_fma_f32 v134, v18, v134, v22
	v_fma_f32 v135, v19, v135, v23
	s_cmp_le_u32 s11, 3
	s_cbranch_scc1 .Llf_pre_done
	v_fma_f32 v132, v24, v132, v28
	v_fma_f32 v133, v25, v133, v29
	v_fma_f32 v134, v26, v134, v30
	v_fma_f32 v135, v27, v135, v31
	s_cmp_le_u32 s11, 4
	s_cbranch_scc1 .Llf_pre_done
	v_fma_f32 v132, v32, v132, v36
	v_fma_f32 v133, v33, v133, v37
	v_fma_f32 v134, v34, v134, v38
	v_fma_f32 v135, v35, v135, v39
	s_cmp_le_u32 s11, 5
	s_cbranch_scc1 .Llf_pre_done
	v_fma_f32 v132, v40, v132, v44
	v_fma_f32 v133, v41, v133, v45
	v_fma_f32 v134, v42, v134, v46
	v_fma_f32 v135, v43, v135, v47
	s_cmp_le_u32 s11, 6
	s_cbranch_scc1 .Llf_pre_done
	v_fma_f32 v132, v48, v132, v52
	v_fma_f32 v133, v49, v133, v53
	v_fma_f32 v134, v50, v134, v54
	v_fma_f32 v135, v51, v135, v55
	s_cmp_le_u32 s11, 7
	s_cbranch_scc1 .Llf_pre_done
	v_fma_f32 v132, v56, v132, v60
	v_fma_f32 v133, v57, v133, v61
	v_fma_f32 v134, v58, v134, v62
	v_fma_f32 v135, v59, v135, v63
	s_cmp_le_u32 s11, 8
	s_cbranch_scc1 .Llf_pre_done
	v_fma_f32 v132, v64, v132, v68
	v_fma_f32 v133, v65, v133, v69
	v_fma_f32 v134, v66, v134, v70
	v_fma_f32 v135, v67, v135, v71
	s_cmp_le_u32 s11, 9
	s_cbranch_scc1 .Llf_pre_done
	v_fma_f32 v132, v72, v132, v76
	v_fma_f32 v133, v73, v133, v77
	v_fma_f32 v134, v74, v134, v78
	v_fma_f32 v135, v75, v135, v79
	s_cmp_le_u32 s11, 10
	s_cbranch_scc1 .Llf_pre_done
	v_fma_f32 v132, v80, v132, v84
	v_fma_f32 v133, v81, v133, v85
	v_fma_f32 v134, v82, v134, v86
	v_fma_f32 v135, v83, v135, v87
	s_cmp_le_u32 s11, 11
	s_cbranch_scc1 .Llf_pre_done
	v_fma_f32 v132, v88, v132, v92
	v_fma_f32 v133, v89, v133, v93
	v_fma_f32 v134, v90, v134, v94
	v_fma_f32 v135, v91, v135, v95
	s_cmp_le_u32 s11, 12
	s_cbranch_scc1 .Llf_pre_done
	v_fma_f32 v132, v96, v132, v100
	v_fma_f32 v133, v97, v133, v101
	v_fma_f32 v134, v98, v134, v102
	v_fma_f32 v135, v99, v135, v103
	s_cmp_le_u32 s11, 13
	s_cbranch_scc1 .Llf_pre_done
	v_fma_f32 v132, v104, v132, v108
	v_fma_f32 v133, v105, v133, v109
	v_fma_f32 v134, v106, v134, v110
	v_fma_f32 v135, v107, v135, v111
	s_cmp_le_u32 s11, 14
	s_cbranch_scc1 .Llf_pre_done
	v_fma_f32 v132, v112, v132, v116
	v_fma_f32 v133, v113, v133, v117
	v_fma_f32 v134, v114, v134, v118
	v_fma_f32 v135, v115, v135, v119
	s_cmp_le_u32 s11, 15
	s_cbranch_scc1 .Llf_pre_done
	v_fma_f32 v132, v120, v132, v124
	v_fma_f32 v133, v121, v133, v125
	v_fma_f32 v134, v122, v134, v126
	v_fma_f32 v135, v123, v135, v127
	s_add_u32 s10, s10, 16
	s_branch .Llf_pre
; __device__ __forceinline__ float bf2f(u16 h) { return __uint_as_float(((unsigned)h) << 16); }
; __device__ __forceinline__ void lru_fix_phase(const Params& p, const XcdBarrier& xb) {
;     ...
;     for (int u = 0; u < 4; u++) {
;       const int li = li0 + u;
;       const int r0 = li * 16;
; #pragma unroll 8
;       for (int q = 0; q < 16; q++) {
;         const int row = r0 + q;
;         float hv = HL[(size_t)row * 512 + ch] + CA[(size_t)row * 512 + ch] * carry;
;         float gate = geluf_(bf2f(Q[(size_t)row * 2048 + 1024 + ch]));
;         Y[(size_t)row * 1024 + 512 + ch] = f2bf(hv * gate);
.Llf_pre_done:
	s_add_u32 s7, s7, s17
	s_lshl_b32 s7, s7, 4
	s_lshl_b32 s19, s7, 11
	s_add_u32 s20, s96, 0xd408100
	s_addc_u32 s21, s97, 0
	s_add_u32 s20, s20, s19
	s_addc_u32 s21, s21, 0
	s_add_u32 s22, s96, 0xb308100
	s_addc_u32 s23, s97, 0
	s_add_u32 s22, s22, s19
	s_addc_u32 s23, s23, 0
	s_add_u32 s24, s96, 0x5008500
	s_addc_u32 s25, s97, 0
	s_add_u32 s24, s24, s19
	s_addc_u32 s25, s25, 0
	s_lshl_b32 s19, s7, 12
	s_add_u32 s26, s96, 0x7108900
	s_addc_u32 s27, s97, 0
	s_add_u32 s26, s26, s19
	s_addc_u32 s27, s27, 0
	global_load_dwordx4 v[0:3], v129, s[20:21]
	global_load_dwordx4 v[4:7], v129, s[22:23]
	global_load_dwordx2 v[8:9], v130, s[26:27]
	s_add_u32 s20, s20, 0x800
	s_addc_u32 s21, s21, 0
	s_add_u32 s22, s22, 0x800
	s_addc_u32 s23, s23, 0
	s_add_u32 s26, s26, 0x1000
	s_addc_u32 s27, s27, 0
	global_load_dwordx4 v[10:13], v129, s[20:21]
	global_load_dwordx4 v[14:17], v129, s[22:23]
	global_load_dwordx2 v[18:19], v130, s[26:27]
	s_add_u32 s20, s20, 0x800
	s_addc_u32 s21, s21, 0
	s_add_u32 s22, s22, 0x800
	s_addc_u32 s23, s23, 0
	s_add_u32 s26, s26, 0x1000
	s_addc_u32 s27, s27, 0
	global_load_dwordx4 v[20:23], v129, s[20:21]
	global_load_dwordx4 v[24:27], v129, s[22:23]
	global_load_dwordx2 v[28:29], v130, s[26:27]
	s_add_u32 s20, s20, 0x800
	s_addc_u32 s21, s21, 0
	s_add_u32 s22, s22, 0x800
	s_addc_u32 s23, s23, 0
	s_add_u32 s26, s26, 0x1000
	s_addc_u32 s27, s27, 0
	global_load_dwordx4 v[30:33], v129, s[20:21]
	global_load_dwordx4 v[34:37], v129, s[22:23]
	global_load_dwordx2 v[38:39], v130, s[26:27]
	s_add_u32 s20, s20, 0x800
	s_addc_u32 s21, s21, 0
	s_add_u32 s22, s22, 0x800
	s_addc_u32 s23, s23, 0
	s_add_u32 s26, s26, 0x1000
	s_addc_u32 s27, s27, 0
	global_load_dwordx4 v[40:43], v129, s[20:21]
	global_load_dwordx4 v[44:47], v129, s[22:23]
	global_load_dwordx2 v[48:49], v130, s[26:27]
	s_add_u32 s20, s20, 0x800
	s_addc_u32 s21, s21, 0
	s_add_u32 s22, s22, 0x800
	s_addc_u32 s23, s23, 0
	s_add_u32 s26, s26, 0x1000
	s_addc_u32 s27, s27, 0
	global_load_dwordx4 v[50:53], v129, s[20:21]
	global_load_dwordx4 v[54:57], v129, s[22:23]
	global_load_dwordx2 v[58:59], v130, s[26:27]
	s_add_u32 s20, s20, 0x800
	s_addc_u32 s21, s21, 0
	s_add_u32 s22, s22, 0x800
	s_addc_u32 s23, s23, 0
	s_add_u32 s26, s26, 0x1000
	s_addc_u32 s27, s27, 0
	global_load_dwordx4 v[60:63], v129, s[20:21]
	global_load_dwordx4 v[64:67], v129, s[22:23]
	global_load_dwordx2 v[68:69], v130, s[26:27]
	s_add_u32 s20, s20, 0x800
	s_addc_u32 s21, s21, 0
	s_add_u32 s22, s22, 0x800
	s_addc_u32 s23, s23, 0
	s_add_u32 s26, s26, 0x1000
	s_addc_u32 s27, s27, 0
	global_load_dwordx4 v[70:73], v129, s[20:21]
	global_load_dwordx4 v[74:77], v129, s[22:23]
	global_load_dwordx2 v[78:79], v130, s[26:27]
	s_add_u32 s20, s20, 0x800
	s_addc_u32 s21, s21, 0
	s_add_u32 s22, s22, 0x800
	s_addc_u32 s23, s23, 0
	s_add_u32 s26, s26, 0x1000
	s_addc_u32 s27, s27, 0
	s_waitcnt vmcnt(0)
	v_lshlrev_b32_e32 v136, 16, v8
	v_and_b32_e32 v137, 0xffff0000, v8
	v_lshlrev_b32_e32 v138, 16, v9
	v_and_b32_e32 v139, 0xffff0000, v9
	v_mul_f32_e32 v140, 0x3d372713, v136
	v_mul_f32_e32 v141, 0x3d372713, v137
	v_mul_f32_e32 v142, 0x3d372713, v138
	v_mul_f32_e32 v143, 0x3d372713, v139
	v_mul_f32_e32 v140, v140, v136
	v_mul_f32_e32 v141, v141, v137
	v_mul_f32_e32 v142, v142, v138
	v_mul_f32_e32 v143, v143, v139
	v_fma_f32 v140, v140, v136, v136
	v_fma_f32 v141, v141, v137, v137
	v_fma_f32 v142, v142, v138, v138
	v_fma_f32 v143, v143, v139, v139
	v_mul_f32_e32 v140, 0x3f4c422a, v140
	v_mul_f32_e32 v141, 0x3f4c422a, v141
	v_mul_f32_e32 v142, 0x3f4c422a, v142
	v_mul_f32_e32 v143, 0x3f4c422a, v143
	v_add_f32_e32 v140, v140, v140
	v_add_f32_e32 v141, v141, v141
	v_add_f32_e32 v142, v142, v142
	v_add_f32_e32 v143, v143, v143
	v_mul_f32_e32 v140, 0x3fb8aa3b, v140
	v_mul_f32_e32 v141, 0x3fb8aa3b, v141
	v_mul_f32_e32 v142, 0x3fb8aa3b, v142
	v_mul_f32_e32 v143, 0x3fb8aa3b, v143
	v_exp_f32_e32 v140, v140
	v_exp_f32_e32 v141, v141
	v_exp_f32_e32 v142, v142
	v_exp_f32_e32 v143, v143
	v_mul_f32_e32 v136, 0.5, v136
	v_mul_f32_e32 v137, 0.5, v137
	v_mul_f32_e32 v138, 0.5, v138
	v_mul_f32_e32 v139, 0.5, v139
	v_add_f32_e32 v140, 1.0, v140
	v_add_f32_e32 v141, 1.0, v141
	v_add_f32_e32 v142, 1.0, v142
	v_add_f32_e32 v143, 1.0, v143
	v_rcp_f32_e32 v140, v140
	v_rcp_f32_e32 v141, v141
	v_rcp_f32_e32 v142, v142
	v_rcp_f32_e32 v143, v143
	v_fmac_f32_e32 v0, v132, v4
	v_fmac_f32_e32 v1, v133, v5
	v_fmac_f32_e32 v2, v134, v6
	v_fmac_f32_e32 v3, v135, v7
	v_fma_f32 v140, v140, -2.0, 1.0
	v_fma_f32 v141, v141, -2.0, 1.0
	v_fma_f32 v142, v142, -2.0, 1.0
	v_fma_f32 v143, v143, -2.0, 1.0
	v_add_f32_e32 v140, 1.0, v140
	v_add_f32_e32 v141, 1.0, v141
	v_add_f32_e32 v142, 1.0, v142
	v_add_f32_e32 v143, 1.0, v143
	v_mul_f32_e32 v136, v136, v140
	v_mul_f32_e32 v137, v137, v141
	v_mul_f32_e32 v138, v138, v142
	v_mul_f32_e32 v139, v139, v143
	v_mul_f32_e32 v136, v0, v136
	v_mul_f32_e32 v137, v1, v137
	v_mul_f32_e32 v138, v2, v138
	v_mul_f32_e32 v139, v3, v139
	v_cvt_pk_bf16_f32 v140, v136, v137
	v_cvt_pk_bf16_f32 v141, v138, v139
	global_store_dwordx2 v130, v[140:141], s[24:25]
	s_add_u32 s24, s24, 0x800
	s_addc_u32 s25, s25, 0
	s_nop 0
	v_lshlrev_b32_e32 v136, 16, v18
	v_and_b32_e32 v137, 0xffff0000, v18
	v_lshlrev_b32_e32 v138, 16, v19
	v_and_b32_e32 v139, 0xffff0000, v19
	v_mul_f32_e32 v140, 0x3d372713, v136
	v_mul_f32_e32 v141, 0x3d372713, v137
	v_mul_f32_e32 v142, 0x3d372713, v138
	v_mul_f32_e32 v143, 0x3d372713, v139
	v_mul_f32_e32 v140, v140, v136
	v_mul_f32_e32 v141, v141, v137
	v_mul_f32_e32 v142, v142, v138
	v_mul_f32_e32 v143, v143, v139
	v_fma_f32 v140, v140, v136, v136
	v_fma_f32 v141, v141, v137, v137
	v_fma_f32 v142, v142, v138, v138
; __device__ __forceinline__ float bf2f(u16 h) { return __uint_as_float(((unsigned)h) << 16); }
; __device__ __forceinline__ void lru_fix_phase(const Params& p, const XcdBarrier& xb) {
;     ...
;       for (int q = 0; q < 16; q++) {
;         const int row = r0 + q;
;         float hv = HL[(size_t)row * 512 + ch] + CA[(size_t)row * 512 + ch] * carry;
;         float gate = geluf_(bf2f(Q[(size_t)row * 2048 + 1024 + ch]));
;         Y[(size_t)row * 1024 + 512 + ch] = f2bf(hv * gate);
	v_fma_f32 v143, v143, v139, v139
	v_mul_f32_e32 v140, 0x3f4c422a, v140
	v_mul_f32_e32 v141, 0x3f4c422a, v141
	v_mul_f32_e32 v142, 0x3f4c422a, v142
	v_mul_f32_e32 v143, 0x3f4c422a, v143
	v_add_f32_e32 v140, v140, v140
	v_add_f32_e32 v141, v141, v141
	v_add_f32_e32 v142, v142, v142
	v_add_f32_e32 v143, v143, v143
	v_mul_f32_e32 v140, 0x3fb8aa3b, v140
	v_mul_f32_e32 v141, 0x3fb8aa3b, v141
	v_mul_f32_e32 v142, 0x3fb8aa3b, v142
	v_mul_f32_e32 v143, 0x3fb8aa3b, v143
	v_exp_f32_e32 v140, v140
	v_exp_f32_e32 v141, v141
	v_exp_f32_e32 v142, v142
	v_exp_f32_e32 v143, v143
	v_mul_f32_e32 v136, 0.5, v136
	v_mul_f32_e32 v137, 0.5, v137
	v_mul_f32_e32 v138, 0.5, v138
	v_mul_f32_e32 v139, 0.5, v139
	v_add_f32_e32 v140, 1.0, v140
	v_add_f32_e32 v141, 1.0, v141
	v_add_f32_e32 v142, 1.0, v142
	v_add_f32_e32 v143, 1.0, v143
	v_rcp_f32_e32 v140, v140
	v_rcp_f32_e32 v141, v141
	v_rcp_f32_e32 v142, v142
	v_rcp_f32_e32 v143, v143
	v_fmac_f32_e32 v10, v132, v14
	v_fmac_f32_e32 v11, v133, v15
	v_fmac_f32_e32 v12, v134, v16
	v_fmac_f32_e32 v13, v135, v17
	v_fma_f32 v140, v140, -2.0, 1.0
	v_fma_f32 v141, v141, -2.0, 1.0
	v_fma_f32 v142, v142, -2.0, 1.0
	v_fma_f32 v143, v143, -2.0, 1.0
	v_add_f32_e32 v140, 1.0, v140
	v_add_f32_e32 v141, 1.0, v141
	v_add_f32_e32 v142, 1.0, v142
	v_add_f32_e32 v143, 1.0, v143
	v_mul_f32_e32 v136, v136, v140
	v_mul_f32_e32 v137, v137, v141
	v_mul_f32_e32 v138, v138, v142
	v_mul_f32_e32 v139, v139, v143
	v_mul_f32_e32 v136, v10, v136
	v_mul_f32_e32 v137, v11, v137
	v_mul_f32_e32 v138, v12, v138
	v_mul_f32_e32 v139, v13, v139
	v_cvt_pk_bf16_f32 v140, v136, v137
	v_cvt_pk_bf16_f32 v141, v138, v139
	global_store_dwordx2 v130, v[140:141], s[24:25]
	s_add_u32 s24, s24, 0x800
	s_addc_u32 s25, s25, 0
	s_nop 0
	v_lshlrev_b32_e32 v136, 16, v28
	v_and_b32_e32 v137, 0xffff0000, v28
	v_lshlrev_b32_e32 v138, 16, v29
	v_and_b32_e32 v139, 0xffff0000, v29
	v_mul_f32_e32 v140, 0x3d372713, v136
	v_mul_f32_e32 v141, 0x3d372713, v137
	v_mul_f32_e32 v142, 0x3d372713, v138
	v_mul_f32_e32 v143, 0x3d372713, v139
	v_mul_f32_e32 v140, v140, v136
	v_mul_f32_e32 v141, v141, v137
	v_mul_f32_e32 v142, v142, v138
	v_mul_f32_e32 v143, v143, v139
	v_fma_f32 v140, v140, v136, v136
	v_fma_f32 v141, v141, v137, v137
	v_fma_f32 v142, v142, v138, v138
	v_fma_f32 v143, v143, v139, v139
	v_mul_f32_e32 v140, 0x3f4c422a, v140
	v_mul_f32_e32 v141, 0x3f4c422a, v141
	v_mul_f32_e32 v142, 0x3f4c422a, v142
	v_mul_f32_e32 v143, 0x3f4c422a, v143
	v_add_f32_e32 v140, v140, v140
	v_add_f32_e32 v141, v141, v141
	v_add_f32_e32 v142, v142, v142
	v_add_f32_e32 v143, v143, v143
	v_mul_f32_e32 v140, 0x3fb8aa3b, v140
	v_mul_f32_e32 v141, 0x3fb8aa3b, v141
	v_mul_f32_e32 v142, 0x3fb8aa3b, v142
	v_mul_f32_e32 v143, 0x3fb8aa3b, v143
	v_exp_f32_e32 v140, v140
	v_exp_f32_e32 v141, v141
	v_exp_f32_e32 v142, v142
	v_exp_f32_e32 v143, v143
	v_mul_f32_e32 v136, 0.5, v136
	v_mul_f32_e32 v137, 0.5, v137
	v_mul_f32_e32 v138, 0.5, v138
	v_mul_f32_e32 v139, 0.5, v139
	v_add_f32_e32 v140, 1.0, v140
	v_add_f32_e32 v141, 1.0, v141
	v_add_f32_e32 v142, 1.0, v142
	v_add_f32_e32 v143, 1.0, v143
	v_rcp_f32_e32 v140, v140
	v_rcp_f32_e32 v141, v141
	v_rcp_f32_e32 v142, v142
	v_rcp_f32_e32 v143, v143
	v_fmac_f32_e32 v20, v132, v24
	v_fmac_f32_e32 v21, v133, v25
	v_fmac_f32_e32 v22, v134, v26
	v_fmac_f32_e32 v23, v135, v27
	v_fma_f32 v140, v140, -2.0, 1.0
	v_fma_f32 v141, v141, -2.0, 1.0
	v_fma_f32 v142, v142, -2.0, 1.0
	v_fma_f32 v143, v143, -2.0, 1.0
	v_add_f32_e32 v140, 1.0, v140
	v_add_f32_e32 v141, 1.0, v141
	v_add_f32_e32 v142, 1.0, v142
	v_add_f32_e32 v143, 1.0, v143
	v_mul_f32_e32 v136, v136, v140
	v_mul_f32_e32 v137, v137, v141
	v_mul_f32_e32 v138, v138, v142
	v_mul_f32_e32 v139, v139, v143
	v_mul_f32_e32 v136, v20, v136
	v_mul_f32_e32 v137, v21, v137
	v_mul_f32_e32 v138, v22, v138
	v_mul_f32_e32 v139, v23, v139
	v_cvt_pk_bf16_f32 v140, v136, v137
	v_cvt_pk_bf16_f32 v141, v138, v139
	global_store_dwordx2 v130, v[140:141], s[24:25]
	s_add_u32 s24, s24, 0x800
	s_addc_u32 s25, s25, 0
	s_nop 0
	v_lshlrev_b32_e32 v136, 16, v38
	v_and_b32_e32 v137, 0xffff0000, v38
	v_lshlrev_b32_e32 v138, 16, v39
	v_and_b32_e32 v139, 0xffff0000, v39
	v_mul_f32_e32 v140, 0x3d372713, v136
	v_mul_f32_e32 v141, 0x3d372713, v137
	v_mul_f32_e32 v142, 0x3d372713, v138
	v_mul_f32_e32 v143, 0x3d372713, v139
	v_mul_f32_e32 v140, v140, v136
	v_mul_f32_e32 v141, v141, v137
	v_mul_f32_e32 v142, v142, v138
	v_mul_f32_e32 v143, v143, v139
	v_fma_f32 v140, v140, v136, v136
	v_fma_f32 v141, v141, v137, v137
	v_fma_f32 v142, v142, v138, v138
	v_fma_f32 v143, v143, v139, v139
	v_mul_f32_e32 v140, 0x3f4c422a, v140
	v_mul_f32_e32 v141, 0x3f4c422a, v141
	v_mul_f32_e32 v142, 0x3f4c422a, v142
	v_mul_f32_e32 v143, 0x3f4c422a, v143
	v_add_f32_e32 v140, v140, v140
	v_add_f32_e32 v141, v141, v141
	v_add_f32_e32 v142, v142, v142
	v_add_f32_e32 v143, v143, v143
	v_mul_f32_e32 v140, 0x3fb8aa3b, v140
	v_mul_f32_e32 v141, 0x3fb8aa3b, v141
	v_mul_f32_e32 v142, 0x3fb8aa3b, v142
	v_mul_f32_e32 v143, 0x3fb8aa3b, v143
	v_exp_f32_e32 v140, v140
	v_exp_f32_e32 v141, v141
	v_exp_f32_e32 v142, v142
	v_exp_f32_e32 v143, v143
	v_mul_f32_e32 v136, 0.5, v136
	v_mul_f32_e32 v137, 0.5, v137
	v_mul_f32_e32 v138, 0.5, v138
	v_mul_f32_e32 v139, 0.5, v139
	v_add_f32_e32 v140, 1.0, v140
	v_add_f32_e32 v141, 1.0, v141
	v_add_f32_e32 v142, 1.0, v142
	v_add_f32_e32 v143, 1.0, v143
	v_rcp_f32_e32 v140, v140
	v_rcp_f32_e32 v141, v141
	v_rcp_f32_e32 v142, v142
	v_rcp_f32_e32 v143, v143
	v_fmac_f32_e32 v30, v132, v34
	v_fmac_f32_e32 v31, v133, v35
	v_fmac_f32_e32 v32, v134, v36
	v_fmac_f32_e32 v33, v135, v37
	v_fma_f32 v140, v140, -2.0, 1.0
	v_fma_f32 v141, v141, -2.0, 1.0
; __device__ __forceinline__ float bf2f(u16 h) { return __uint_as_float(((unsigned)h) << 16); }
; __device__ __forceinline__ void lru_fix_phase(const Params& p, const XcdBarrier& xb) {
;     ...
;       for (int q = 0; q < 16; q++) {
;         const int row = r0 + q;
;         float hv = HL[(size_t)row * 512 + ch] + CA[(size_t)row * 512 + ch] * carry;
;         float gate = geluf_(bf2f(Q[(size_t)row * 2048 + 1024 + ch]));
;         Y[(size_t)row * 1024 + 512 + ch] = f2bf(hv * gate);
	v_fma_f32 v142, v142, -2.0, 1.0
	v_fma_f32 v143, v143, -2.0, 1.0
	v_add_f32_e32 v140, 1.0, v140
	v_add_f32_e32 v141, 1.0, v141
	v_add_f32_e32 v142, 1.0, v142
	v_add_f32_e32 v143, 1.0, v143
	v_mul_f32_e32 v136, v136, v140
	v_mul_f32_e32 v137, v137, v141
	v_mul_f32_e32 v138, v138, v142
	v_mul_f32_e32 v139, v139, v143
	v_mul_f32_e32 v136, v30, v136
	v_mul_f32_e32 v137, v31, v137
	v_mul_f32_e32 v138, v32, v138
	v_mul_f32_e32 v139, v33, v139
	v_cvt_pk_bf16_f32 v140, v136, v137
	v_cvt_pk_bf16_f32 v141, v138, v139
	global_store_dwordx2 v130, v[140:141], s[24:25]
	s_add_u32 s24, s24, 0x800
	s_addc_u32 s25, s25, 0
	s_nop 0
	v_lshlrev_b32_e32 v136, 16, v48
	v_and_b32_e32 v137, 0xffff0000, v48
	v_lshlrev_b32_e32 v138, 16, v49
	v_and_b32_e32 v139, 0xffff0000, v49
	v_mul_f32_e32 v140, 0x3d372713, v136
	v_mul_f32_e32 v141, 0x3d372713, v137
	v_mul_f32_e32 v142, 0x3d372713, v138
	v_mul_f32_e32 v143, 0x3d372713, v139
	v_mul_f32_e32 v140, v140, v136
	v_mul_f32_e32 v141, v141, v137
	v_mul_f32_e32 v142, v142, v138
	v_mul_f32_e32 v143, v143, v139
	v_fma_f32 v140, v140, v136, v136
	v_fma_f32 v141, v141, v137, v137
	v_fma_f32 v142, v142, v138, v138
	v_fma_f32 v143, v143, v139, v139
	v_mul_f32_e32 v140, 0x3f4c422a, v140
	v_mul_f32_e32 v141, 0x3f4c422a, v141
	v_mul_f32_e32 v142, 0x3f4c422a, v142
	v_mul_f32_e32 v143, 0x3f4c422a, v143
	v_add_f32_e32 v140, v140, v140
	v_add_f32_e32 v141, v141, v141
	v_add_f32_e32 v142, v142, v142
	v_add_f32_e32 v143, v143, v143
	v_mul_f32_e32 v140, 0x3fb8aa3b, v140
	v_mul_f32_e32 v141, 0x3fb8aa3b, v141
	v_mul_f32_e32 v142, 0x3fb8aa3b, v142
	v_mul_f32_e32 v143, 0x3fb8aa3b, v143
	v_exp_f32_e32 v140, v140
	v_exp_f32_e32 v141, v141
	v_exp_f32_e32 v142, v142
	v_exp_f32_e32 v143, v143
	v_mul_f32_e32 v136, 0.5, v136
	v_mul_f32_e32 v137, 0.5, v137
	v_mul_f32_e32 v138, 0.5, v138
	v_mul_f32_e32 v139, 0.5, v139
	v_add_f32_e32 v140, 1.0, v140
	v_add_f32_e32 v141, 1.0, v141
	v_add_f32_e32 v142, 1.0, v142
	v_add_f32_e32 v143, 1.0, v143
	v_rcp_f32_e32 v140, v140
	v_rcp_f32_e32 v141, v141
	v_rcp_f32_e32 v142, v142
	v_rcp_f32_e32 v143, v143
	v_fmac_f32_e32 v40, v132, v44
	v_fmac_f32_e32 v41, v133, v45
	v_fmac_f32_e32 v42, v134, v46
	v_fmac_f32_e32 v43, v135, v47
	v_fma_f32 v140, v140, -2.0, 1.0
	v_fma_f32 v141, v141, -2.0, 1.0
	v_fma_f32 v142, v142, -2.0, 1.0
	v_fma_f32 v143, v143, -2.0, 1.0
	v_add_f32_e32 v140, 1.0, v140
	v_add_f32_e32 v141, 1.0, v141
	v_add_f32_e32 v142, 1.0, v142
	v_add_f32_e32 v143, 1.0, v143
	v_mul_f32_e32 v136, v136, v140
	v_mul_f32_e32 v137, v137, v141
	v_mul_f32_e32 v138, v138, v142
	v_mul_f32_e32 v139, v139, v143
	v_mul_f32_e32 v136, v40, v136
	v_mul_f32_e32 v137, v41, v137
	v_mul_f32_e32 v138, v42, v138
	v_mul_f32_e32 v139, v43, v139
	v_cvt_pk_bf16_f32 v140, v136, v137
	v_cvt_pk_bf16_f32 v141, v138, v139
	global_store_dwordx2 v130, v[140:141], s[24:25]
	s_add_u32 s24, s24, 0x800
	s_addc_u32 s25, s25, 0
	s_nop 0
	v_lshlrev_b32_e32 v136, 16, v58
	v_and_b32_e32 v137, 0xffff0000, v58
	v_lshlrev_b32_e32 v138, 16, v59
	v_and_b32_e32 v139, 0xffff0000, v59
	v_mul_f32_e32 v140, 0x3d372713, v136
	v_mul_f32_e32 v141, 0x3d372713, v137
	v_mul_f32_e32 v142, 0x3d372713, v138
	v_mul_f32_e32 v143, 0x3d372713, v139
	v_mul_f32_e32 v140, v140, v136
	v_mul_f32_e32 v141, v141, v137
	v_mul_f32_e32 v142, v142, v138
	v_mul_f32_e32 v143, v143, v139
	v_fma_f32 v140, v140, v136, v136
	v_fma_f32 v141, v141, v137, v137
	v_fma_f32 v142, v142, v138, v138
	v_fma_f32 v143, v143, v139, v139
	v_mul_f32_e32 v140, 0x3f4c422a, v140
	v_mul_f32_e32 v141, 0x3f4c422a, v141
	v_mul_f32_e32 v142, 0x3f4c422a, v142
	v_mul_f32_e32 v143, 0x3f4c422a, v143
	v_add_f32_e32 v140, v140, v140
	v_add_f32_e32 v141, v141, v141
	v_add_f32_e32 v142, v142, v142
	v_add_f32_e32 v143, v143, v143
	v_mul_f32_e32 v140, 0x3fb8aa3b, v140
	v_mul_f32_e32 v141, 0x3fb8aa3b, v141
	v_mul_f32_e32 v142, 0x3fb8aa3b, v142
	v_mul_f32_e32 v143, 0x3fb8aa3b, v143
	v_exp_f32_e32 v140, v140
	v_exp_f32_e32 v141, v141
	v_exp_f32_e32 v142, v142
	v_exp_f32_e32 v143, v143
	v_mul_f32_e32 v136, 0.5, v136
	v_mul_f32_e32 v137, 0.5, v137
	v_mul_f32_e32 v138, 0.5, v138
	v_mul_f32_e32 v139, 0.5, v139
	v_add_f32_e32 v140, 1.0, v140
	v_add_f32_e32 v141, 1.0, v141
	v_add_f32_e32 v142, 1.0, v142
	v_add_f32_e32 v143, 1.0, v143
	v_rcp_f32_e32 v140, v140
	v_rcp_f32_e32 v141, v141
	v_rcp_f32_e32 v142, v142
	v_rcp_f32_e32 v143, v143
	v_fmac_f32_e32 v50, v132, v54
	v_fmac_f32_e32 v51, v133, v55
	v_fmac_f32_e32 v52, v134, v56
	v_fmac_f32_e32 v53, v135, v57
	v_fma_f32 v140, v140, -2.0, 1.0
	v_fma_f32 v141, v141, -2.0, 1.0
	v_fma_f32 v142, v142, -2.0, 1.0
	v_fma_f32 v143, v143, -2.0, 1.0
	v_add_f32_e32 v140, 1.0, v140
	v_add_f32_e32 v141, 1.0, v141
	v_add_f32_e32 v142, 1.0, v142
	v_add_f32_e32 v143, 1.0, v143
	v_mul_f32_e32 v136, v136, v140
	v_mul_f32_e32 v137, v137, v141
	v_mul_f32_e32 v138, v138, v142
	v_mul_f32_e32 v139, v139, v143
	v_mul_f32_e32 v136, v50, v136
	v_mul_f32_e32 v137, v51, v137
	v_mul_f32_e32 v138, v52, v138
	v_mul_f32_e32 v139, v53, v139
	v_cvt_pk_bf16_f32 v140, v136, v137
	v_cvt_pk_bf16_f32 v141, v138, v139
	global_store_dwordx2 v130, v[140:141], s[24:25]
	s_add_u32 s24, s24, 0x800
	s_addc_u32 s25, s25, 0
	s_nop 0
	v_lshlrev_b32_e32 v136, 16, v68
	v_and_b32_e32 v137, 0xffff0000, v68
	v_lshlrev_b32_e32 v138, 16, v69
	v_and_b32_e32 v139, 0xffff0000, v69
	v_mul_f32_e32 v140, 0x3d372713, v136
	v_mul_f32_e32 v141, 0x3d372713, v137
	v_mul_f32_e32 v142, 0x3d372713, v138
	v_mul_f32_e32 v143, 0x3d372713, v139
	v_mul_f32_e32 v140, v140, v136
	v_mul_f32_e32 v141, v141, v137
	v_mul_f32_e32 v142, v142, v138
	v_mul_f32_e32 v143, v143, v139
	v_fma_f32 v140, v140, v136, v136
	v_fma_f32 v141, v141, v137, v137
; __device__ __forceinline__ float bf2f(u16 h) { return __uint_as_float(((unsigned)h) << 16); }
; __device__ __forceinline__ void lru_fix_phase(const Params& p, const XcdBarrier& xb) {
;     ...
;       const int r0 = li * 16;
; #pragma unroll 8
;       for (int q = 0; q < 16; q++) {
;         const int row = r0 + q;
;         float hv = HL[(size_t)row * 512 + ch] + CA[(size_t)row * 512 + ch] * carry;
;         float gate = geluf_(bf2f(Q[(size_t)row * 2048 + 1024 + ch]));
;         Y[(size_t)row * 1024 + 512 + ch] = f2bf(hv * gate);
	v_fma_f32 v142, v142, v138, v138
	v_fma_f32 v143, v143, v139, v139
	v_mul_f32_e32 v140, 0x3f4c422a, v140
	v_mul_f32_e32 v141, 0x3f4c422a, v141
	v_mul_f32_e32 v142, 0x3f4c422a, v142
	v_mul_f32_e32 v143, 0x3f4c422a, v143
	v_add_f32_e32 v140, v140, v140
	v_add_f32_e32 v141, v141, v141
	v_add_f32_e32 v142, v142, v142
	v_add_f32_e32 v143, v143, v143
	v_mul_f32_e32 v140, 0x3fb8aa3b, v140
	v_mul_f32_e32 v141, 0x3fb8aa3b, v141
	v_mul_f32_e32 v142, 0x3fb8aa3b, v142
	v_mul_f32_e32 v143, 0x3fb8aa3b, v143
	v_exp_f32_e32 v140, v140
	v_exp_f32_e32 v141, v141
	v_exp_f32_e32 v142, v142
	v_exp_f32_e32 v143, v143
	v_mul_f32_e32 v136, 0.5, v136
	v_mul_f32_e32 v137, 0.5, v137
	v_mul_f32_e32 v138, 0.5, v138
	v_mul_f32_e32 v139, 0.5, v139
	v_add_f32_e32 v140, 1.0, v140
	v_add_f32_e32 v141, 1.0, v141
	v_add_f32_e32 v142, 1.0, v142
	v_add_f32_e32 v143, 1.0, v143
	v_rcp_f32_e32 v140, v140
	v_rcp_f32_e32 v141, v141
	v_rcp_f32_e32 v142, v142
	v_rcp_f32_e32 v143, v143
	v_fmac_f32_e32 v60, v132, v64
	v_fmac_f32_e32 v61, v133, v65
	v_fmac_f32_e32 v62, v134, v66
	v_fmac_f32_e32 v63, v135, v67
	v_fma_f32 v140, v140, -2.0, 1.0
	v_fma_f32 v141, v141, -2.0, 1.0
	v_fma_f32 v142, v142, -2.0, 1.0
	v_fma_f32 v143, v143, -2.0, 1.0
	v_add_f32_e32 v140, 1.0, v140
	v_add_f32_e32 v141, 1.0, v141
	v_add_f32_e32 v142, 1.0, v142
	v_add_f32_e32 v143, 1.0, v143
	v_mul_f32_e32 v136, v136, v140
	v_mul_f32_e32 v137, v137, v141
	v_mul_f32_e32 v138, v138, v142
	v_mul_f32_e32 v139, v139, v143
	v_mul_f32_e32 v136, v60, v136
	v_mul_f32_e32 v137, v61, v137
	v_mul_f32_e32 v138, v62, v138
	v_mul_f32_e32 v139, v63, v139
	v_cvt_pk_bf16_f32 v140, v136, v137
	v_cvt_pk_bf16_f32 v141, v138, v139
	global_store_dwordx2 v130, v[140:141], s[24:25]
	s_add_u32 s24, s24, 0x800
	s_addc_u32 s25, s25, 0
	s_nop 0
	v_lshlrev_b32_e32 v136, 16, v78
	v_and_b32_e32 v137, 0xffff0000, v78
	v_lshlrev_b32_e32 v138, 16, v79
	v_and_b32_e32 v139, 0xffff0000, v79
	v_mul_f32_e32 v140, 0x3d372713, v136
	v_mul_f32_e32 v141, 0x3d372713, v137
	v_mul_f32_e32 v142, 0x3d372713, v138
	v_mul_f32_e32 v143, 0x3d372713, v139
	v_mul_f32_e32 v140, v140, v136
	v_mul_f32_e32 v141, v141, v137
	v_mul_f32_e32 v142, v142, v138
	v_mul_f32_e32 v143, v143, v139
	v_fma_f32 v140, v140, v136, v136
	v_fma_f32 v141, v141, v137, v137
	v_fma_f32 v142, v142, v138, v138
	v_fma_f32 v143, v143, v139, v139
	v_mul_f32_e32 v140, 0x3f4c422a, v140
	v_mul_f32_e32 v141, 0x3f4c422a, v141
	v_mul_f32_e32 v142, 0x3f4c422a, v142
	v_mul_f32_e32 v143, 0x3f4c422a, v143
	v_add_f32_e32 v140, v140, v140
	v_add_f32_e32 v141, v141, v141
	v_add_f32_e32 v142, v142, v142
	v_add_f32_e32 v143, v143, v143
	v_mul_f32_e32 v140, 0x3fb8aa3b, v140
	v_mul_f32_e32 v141, 0x3fb8aa3b, v141
	v_mul_f32_e32 v142, 0x3fb8aa3b, v142
	v_mul_f32_e32 v143, 0x3fb8aa3b, v143
	v_exp_f32_e32 v140, v140
	v_exp_f32_e32 v141, v141
	v_exp_f32_e32 v142, v142
	v_exp_f32_e32 v143, v143
	v_mul_f32_e32 v136, 0.5, v136
	v_mul_f32_e32 v137, 0.5, v137
	v_mul_f32_e32 v138, 0.5, v138
	v_mul_f32_e32 v139, 0.5, v139
	v_add_f32_e32 v140, 1.0, v140
	v_add_f32_e32 v141, 1.0, v141
	v_add_f32_e32 v142, 1.0, v142
	v_add_f32_e32 v143, 1.0, v143
	v_rcp_f32_e32 v140, v140
	v_rcp_f32_e32 v141, v141
	v_rcp_f32_e32 v142, v142
	v_rcp_f32_e32 v143, v143
	v_fmac_f32_e32 v70, v132, v74
	v_fmac_f32_e32 v71, v133, v75
	v_fmac_f32_e32 v72, v134, v76
	v_fmac_f32_e32 v73, v135, v77
	v_fma_f32 v140, v140, -2.0, 1.0
	v_fma_f32 v141, v141, -2.0, 1.0
	v_fma_f32 v142, v142, -2.0, 1.0
	v_fma_f32 v143, v143, -2.0, 1.0
	v_add_f32_e32 v140, 1.0, v140
	v_add_f32_e32 v141, 1.0, v141
	v_add_f32_e32 v142, 1.0, v142
	v_add_f32_e32 v143, 1.0, v143
	v_mul_f32_e32 v136, v136, v140
	v_mul_f32_e32 v137, v137, v141
	v_mul_f32_e32 v138, v138, v142
	v_mul_f32_e32 v139, v139, v143
	v_mul_f32_e32 v136, v70, v136
	v_mul_f32_e32 v137, v71, v137
	v_mul_f32_e32 v138, v72, v138
	v_mul_f32_e32 v139, v73, v139
	v_cvt_pk_bf16_f32 v140, v136, v137
	v_cvt_pk_bf16_f32 v141, v138, v139
	global_store_dwordx2 v130, v[140:141], s[24:25]
	s_add_u32 s24, s24, 0x800
	s_addc_u32 s25, s25, 0
	s_nop 0
	global_load_dwordx4 v[0:3], v129, s[20:21]
	global_load_dwordx4 v[4:7], v129, s[22:23]
	global_load_dwordx2 v[8:9], v130, s[26:27]
	s_add_u32 s20, s20, 0x800
	s_addc_u32 s21, s21, 0
	s_add_u32 s22, s22, 0x800
	s_addc_u32 s23, s23, 0
	s_add_u32 s26, s26, 0x1000
	s_addc_u32 s27, s27, 0
	global_load_dwordx4 v[10:13], v129, s[20:21]
	global_load_dwordx4 v[14:17], v129, s[22:23]
	global_load_dwordx2 v[18:19], v130, s[26:27]
	s_add_u32 s20, s20, 0x800
	s_addc_u32 s21, s21, 0
	s_add_u32 s22, s22, 0x800
	s_addc_u32 s23, s23, 0
	s_add_u32 s26, s26, 0x1000
	s_addc_u32 s27, s27, 0
	global_load_dwordx4 v[20:23], v129, s[20:21]
	global_load_dwordx4 v[24:27], v129, s[22:23]
	global_load_dwordx2 v[28:29], v130, s[26:27]
	s_add_u32 s20, s20, 0x800
	s_addc_u32 s21, s21, 0
	s_add_u32 s22, s22, 0x800
	s_addc_u32 s23, s23, 0
	s_add_u32 s26, s26, 0x1000
	s_addc_u32 s27, s27, 0
	global_load_dwordx4 v[30:33], v129, s[20:21]
	global_load_dwordx4 v[34:37], v129, s[22:23]
	global_load_dwordx2 v[38:39], v130, s[26:27]
	s_add_u32 s20, s20, 0x800
	s_addc_u32 s21, s21, 0
	s_add_u32 s22, s22, 0x800
	s_addc_u32 s23, s23, 0
	s_add_u32 s26, s26, 0x1000
	s_addc_u32 s27, s27, 0
	global_load_dwordx4 v[40:43], v129, s[20:21]
	global_load_dwordx4 v[44:47], v129, s[22:23]
	global_load_dwordx2 v[48:49], v130, s[26:27]
	s_add_u32 s20, s20, 0x800
	s_addc_u32 s21, s21, 0
	s_add_u32 s22, s22, 0x800
	s_addc_u32 s23, s23, 0
	s_add_u32 s26, s26, 0x1000
	s_addc_u32 s27, s27, 0
	global_load_dwordx4 v[50:53], v129, s[20:21]
	global_load_dwordx4 v[54:57], v129, s[22:23]
	global_load_dwordx2 v[58:59], v130, s[26:27]
	s_add_u32 s20, s20, 0x800
	s_addc_u32 s21, s21, 0
	s_add_u32 s22, s22, 0x800
	s_addc_u32 s23, s23, 0
	s_add_u32 s26, s26, 0x1000
	s_addc_u32 s27, s27, 0
	global_load_dwordx4 v[60:63], v129, s[20:21]
	global_load_dwordx4 v[64:67], v129, s[22:23]
	global_load_dwordx2 v[68:69], v130, s[26:27]
	s_add_u32 s20, s20, 0x800
	s_addc_u32 s21, s21, 0
	s_add_u32 s22, s22, 0x800
	s_addc_u32 s23, s23, 0
	s_add_u32 s26, s26, 0x1000
	s_addc_u32 s27, s27, 0
	global_load_dwordx4 v[70:73], v129, s[20:21]
	global_load_dwordx4 v[74:77], v129, s[22:23]
	global_load_dwordx2 v[78:79], v130, s[26:27]
	s_add_u32 s20, s20, 0x800
	s_addc_u32 s21, s21, 0
	s_add_u32 s22, s22, 0x800
	s_addc_u32 s23, s23, 0
	s_add_u32 s26, s26, 0x1000
	s_addc_u32 s27, s27, 0
	s_waitcnt vmcnt(0)
; __device__ __forceinline__ float bf2f(u16 h) { return __uint_as_float(((unsigned)h) << 16); }
; __device__ __forceinline__ void lru_fix_phase(const Params& p, const XcdBarrier& xb) {
;     ...
;       for (int q = 0; q < 16; q++) {
;         const int row = r0 + q;
;         float hv = HL[(size_t)row * 512 + ch] + CA[(size_t)row * 512 + ch] * carry;
;         float gate = geluf_(bf2f(Q[(size_t)row * 2048 + 1024 + ch]));
;         Y[(size_t)row * 1024 + 512 + ch] = f2bf(hv * gate);
	v_lshlrev_b32_e32 v136, 16, v8
	v_and_b32_e32 v137, 0xffff0000, v8
	v_lshlrev_b32_e32 v138, 16, v9
	v_and_b32_e32 v139, 0xffff0000, v9
	v_mul_f32_e32 v140, 0x3d372713, v136
	v_mul_f32_e32 v141, 0x3d372713, v137
	v_mul_f32_e32 v142, 0x3d372713, v138
	v_mul_f32_e32 v143, 0x3d372713, v139
	v_mul_f32_e32 v140, v140, v136
	v_mul_f32_e32 v141, v141, v137
	v_mul_f32_e32 v142, v142, v138
	v_mul_f32_e32 v143, v143, v139
	v_fma_f32 v140, v140, v136, v136
	v_fma_f32 v141, v141, v137, v137
	v_fma_f32 v142, v142, v138, v138
	v_fma_f32 v143, v143, v139, v139
	v_mul_f32_e32 v140, 0x3f4c422a, v140
	v_mul_f32_e32 v141, 0x3f4c422a, v141
	v_mul_f32_e32 v142, 0x3f4c422a, v142
	v_mul_f32_e32 v143, 0x3f4c422a, v143
	v_add_f32_e32 v140, v140, v140
	v_add_f32_e32 v141, v141, v141
	v_add_f32_e32 v142, v142, v142
	v_add_f32_e32 v143, v143, v143
	v_mul_f32_e32 v140, 0x3fb8aa3b, v140
	v_mul_f32_e32 v141, 0x3fb8aa3b, v141
	v_mul_f32_e32 v142, 0x3fb8aa3b, v142
	v_mul_f32_e32 v143, 0x3fb8aa3b, v143
	v_exp_f32_e32 v140, v140
	v_exp_f32_e32 v141, v141
	v_exp_f32_e32 v142, v142
	v_exp_f32_e32 v143, v143
	v_mul_f32_e32 v136, 0.5, v136
	v_mul_f32_e32 v137, 0.5, v137
	v_mul_f32_e32 v138, 0.5, v138
	v_mul_f32_e32 v139, 0.5, v139
	v_add_f32_e32 v140, 1.0, v140
	v_add_f32_e32 v141, 1.0, v141
	v_add_f32_e32 v142, 1.0, v142
	v_add_f32_e32 v143, 1.0, v143
	v_rcp_f32_e32 v140, v140
	v_rcp_f32_e32 v141, v141
	v_rcp_f32_e32 v142, v142
	v_rcp_f32_e32 v143, v143
	v_fmac_f32_e32 v0, v132, v4
	v_fmac_f32_e32 v1, v133, v5
	v_fmac_f32_e32 v2, v134, v6
	v_fmac_f32_e32 v3, v135, v7
	v_fma_f32 v140, v140, -2.0, 1.0
	v_fma_f32 v141, v141, -2.0, 1.0
	v_fma_f32 v142, v142, -2.0, 1.0
	v_fma_f32 v143, v143, -2.0, 1.0
	v_add_f32_e32 v140, 1.0, v140
	v_add_f32_e32 v141, 1.0, v141
	v_add_f32_e32 v142, 1.0, v142
	v_add_f32_e32 v143, 1.0, v143
	v_mul_f32_e32 v136, v136, v140
	v_mul_f32_e32 v137, v137, v141
	v_mul_f32_e32 v138, v138, v142
	v_mul_f32_e32 v139, v139, v143
	v_mul_f32_e32 v136, v0, v136
	v_mul_f32_e32 v137, v1, v137
	v_mul_f32_e32 v138, v2, v138
	v_mul_f32_e32 v139, v3, v139
	v_cvt_pk_bf16_f32 v140, v136, v137
	v_cvt_pk_bf16_f32 v141, v138, v139
	global_store_dwordx2 v130, v[140:141], s[24:25]
	s_add_u32 s24, s24, 0x800
	s_addc_u32 s25, s25, 0
	s_nop 0
	v_lshlrev_b32_e32 v136, 16, v18
	v_and_b32_e32 v137, 0xffff0000, v18
	v_lshlrev_b32_e32 v138, 16, v19
	v_and_b32_e32 v139, 0xffff0000, v19
	v_mul_f32_e32 v140, 0x3d372713, v136
	v_mul_f32_e32 v141, 0x3d372713, v137
	v_mul_f32_e32 v142, 0x3d372713, v138
	v_mul_f32_e32 v143, 0x3d372713, v139
	v_mul_f32_e32 v140, v140, v136
	v_mul_f32_e32 v141, v141, v137
	v_mul_f32_e32 v142, v142, v138
	v_mul_f32_e32 v143, v143, v139
	v_fma_f32 v140, v140, v136, v136
	v_fma_f32 v141, v141, v137, v137
	v_fma_f32 v142, v142, v138, v138
	v_fma_f32 v143, v143, v139, v139
	v_mul_f32_e32 v140, 0x3f4c422a, v140
	v_mul_f32_e32 v141, 0x3f4c422a, v141
	v_mul_f32_e32 v142, 0x3f4c422a, v142
	v_mul_f32_e32 v143, 0x3f4c422a, v143
	v_add_f32_e32 v140, v140, v140
	v_add_f32_e32 v141, v141, v141
	v_add_f32_e32 v142, v142, v142
	v_add_f32_e32 v143, v143, v143
	v_mul_f32_e32 v140, 0x3fb8aa3b, v140
	v_mul_f32_e32 v141, 0x3fb8aa3b, v141
	v_mul_f32_e32 v142, 0x3fb8aa3b, v142
	v_mul_f32_e32 v143, 0x3fb8aa3b, v143
	v_exp_f32_e32 v140, v140
	v_exp_f32_e32 v141, v141
	v_exp_f32_e32 v142, v142
	v_exp_f32_e32 v143, v143
	v_mul_f32_e32 v136, 0.5, v136
	v_mul_f32_e32 v137, 0.5, v137
	v_mul_f32_e32 v138, 0.5, v138
	v_mul_f32_e32 v139, 0.5, v139
	v_add_f32_e32 v140, 1.0, v140
	v_add_f32_e32 v141, 1.0, v141
	v_add_f32_e32 v142, 1.0, v142
	v_add_f32_e32 v143, 1.0, v143
	v_rcp_f32_e32 v140, v140
	v_rcp_f32_e32 v141, v141
	v_rcp_f32_e32 v142, v142
	v_rcp_f32_e32 v143, v143
	v_fmac_f32_e32 v10, v132, v14
	v_fmac_f32_e32 v11, v133, v15
	v_fmac_f32_e32 v12, v134, v16
	v_fmac_f32_e32 v13, v135, v17
	v_fma_f32 v140, v140, -2.0, 1.0
	v_fma_f32 v141, v141, -2.0, 1.0
	v_fma_f32 v142, v142, -2.0, 1.0
	v_fma_f32 v143, v143, -2.0, 1.0
	v_add_f32_e32 v140, 1.0, v140
	v_add_f32_e32 v141, 1.0, v141
	v_add_f32_e32 v142, 1.0, v142
	v_add_f32_e32 v143, 1.0, v143
	v_mul_f32_e32 v136, v136, v140
	v_mul_f32_e32 v137, v137, v141
	v_mul_f32_e32 v138, v138, v142
	v_mul_f32_e32 v139, v139, v143
	v_mul_f32_e32 v136, v10, v136
	v_mul_f32_e32 v137, v11, v137
	v_mul_f32_e32 v138, v12, v138
	v_mul_f32_e32 v139, v13, v139
	v_cvt_pk_bf16_f32 v140, v136, v137
	v_cvt_pk_bf16_f32 v141, v138, v139
	global_store_dwordx2 v130, v[140:141], s[24:25]
	s_add_u32 s24, s24, 0x800
	s_addc_u32 s25, s25, 0
	s_nop 0
	v_lshlrev_b32_e32 v136, 16, v28
	v_and_b32_e32 v137, 0xffff0000, v28
	v_lshlrev_b32_e32 v138, 16, v29
	v_and_b32_e32 v139, 0xffff0000, v29
	v_mul_f32_e32 v140, 0x3d372713, v136
	v_mul_f32_e32 v141, 0x3d372713, v137
	v_mul_f32_e32 v142, 0x3d372713, v138
	v_mul_f32_e32 v143, 0x3d372713, v139
	v_mul_f32_e32 v140, v140, v136
	v_mul_f32_e32 v141, v141, v137
	v_mul_f32_e32 v142, v142, v138
	v_mul_f32_e32 v143, v143, v139
	v_fma_f32 v140, v140, v136, v136
	v_fma_f32 v141, v141, v137, v137
	v_fma_f32 v142, v142, v138, v138
	v_fma_f32 v143, v143, v139, v139
	v_mul_f32_e32 v140, 0x3f4c422a, v140
	v_mul_f32_e32 v141, 0x3f4c422a, v141
	v_mul_f32_e32 v142, 0x3f4c422a, v142
	v_mul_f32_e32 v143, 0x3f4c422a, v143
	v_add_f32_e32 v140, v140, v140
	v_add_f32_e32 v141, v141, v141
	v_add_f32_e32 v142, v142, v142
	v_add_f32_e32 v143, v143, v143
	v_mul_f32_e32 v140, 0x3fb8aa3b, v140
	v_mul_f32_e32 v141, 0x3fb8aa3b, v141
	v_mul_f32_e32 v142, 0x3fb8aa3b, v142
	v_mul_f32_e32 v143, 0x3fb8aa3b, v143
	v_exp_f32_e32 v140, v140
	v_exp_f32_e32 v141, v141
	v_exp_f32_e32 v142, v142
	v_exp_f32_e32 v143, v143
	v_mul_f32_e32 v136, 0.5, v136
	v_mul_f32_e32 v137, 0.5, v137
; __device__ __forceinline__ float bf2f(u16 h) { return __uint_as_float(((unsigned)h) << 16); }
; __device__ __forceinline__ void lru_fix_phase(const Params& p, const XcdBarrier& xb) {
;     ...
;       for (int q = 0; q < 16; q++) {
;         const int row = r0 + q;
;         float hv = HL[(size_t)row * 512 + ch] + CA[(size_t)row * 512 + ch] * carry;
;         float gate = geluf_(bf2f(Q[(size_t)row * 2048 + 1024 + ch]));
;         Y[(size_t)row * 1024 + 512 + ch] = f2bf(hv * gate);
	v_mul_f32_e32 v138, 0.5, v138
	v_mul_f32_e32 v139, 0.5, v139
	v_add_f32_e32 v140, 1.0, v140
	v_add_f32_e32 v141, 1.0, v141
	v_add_f32_e32 v142, 1.0, v142
	v_add_f32_e32 v143, 1.0, v143
	v_rcp_f32_e32 v140, v140
	v_rcp_f32_e32 v141, v141
	v_rcp_f32_e32 v142, v142
	v_rcp_f32_e32 v143, v143
	v_fmac_f32_e32 v20, v132, v24
	v_fmac_f32_e32 v21, v133, v25
	v_fmac_f32_e32 v22, v134, v26
	v_fmac_f32_e32 v23, v135, v27
	v_fma_f32 v140, v140, -2.0, 1.0
	v_fma_f32 v141, v141, -2.0, 1.0
	v_fma_f32 v142, v142, -2.0, 1.0
	v_fma_f32 v143, v143, -2.0, 1.0
	v_add_f32_e32 v140, 1.0, v140
	v_add_f32_e32 v141, 1.0, v141
	v_add_f32_e32 v142, 1.0, v142
	v_add_f32_e32 v143, 1.0, v143
	v_mul_f32_e32 v136, v136, v140
	v_mul_f32_e32 v137, v137, v141
	v_mul_f32_e32 v138, v138, v142
	v_mul_f32_e32 v139, v139, v143
	v_mul_f32_e32 v136, v20, v136
	v_mul_f32_e32 v137, v21, v137
	v_mul_f32_e32 v138, v22, v138
	v_mul_f32_e32 v139, v23, v139
	v_cvt_pk_bf16_f32 v140, v136, v137
	v_cvt_pk_bf16_f32 v141, v138, v139
	global_store_dwordx2 v130, v[140:141], s[24:25]
	s_add_u32 s24, s24, 0x800
	s_addc_u32 s25, s25, 0
	s_nop 0
	v_lshlrev_b32_e32 v136, 16, v38
	v_and_b32_e32 v137, 0xffff0000, v38
	v_lshlrev_b32_e32 v138, 16, v39
	v_and_b32_e32 v139, 0xffff0000, v39
	v_mul_f32_e32 v140, 0x3d372713, v136
	v_mul_f32_e32 v141, 0x3d372713, v137
	v_mul_f32_e32 v142, 0x3d372713, v138
	v_mul_f32_e32 v143, 0x3d372713, v139
	v_mul_f32_e32 v140, v140, v136
	v_mul_f32_e32 v141, v141, v137
	v_mul_f32_e32 v142, v142, v138
	v_mul_f32_e32 v143, v143, v139
	v_fma_f32 v140, v140, v136, v136
	v_fma_f32 v141, v141, v137, v137
	v_fma_f32 v142, v142, v138, v138
	v_fma_f32 v143, v143, v139, v139
	v_mul_f32_e32 v140, 0x3f4c422a, v140
	v_mul_f32_e32 v141, 0x3f4c422a, v141
	v_mul_f32_e32 v142, 0x3f4c422a, v142
	v_mul_f32_e32 v143, 0x3f4c422a, v143
	v_add_f32_e32 v140, v140, v140
	v_add_f32_e32 v141, v141, v141
	v_add_f32_e32 v142, v142, v142
	v_add_f32_e32 v143, v143, v143
	v_mul_f32_e32 v140, 0x3fb8aa3b, v140
	v_mul_f32_e32 v141, 0x3fb8aa3b, v141
	v_mul_f32_e32 v142, 0x3fb8aa3b, v142
	v_mul_f32_e32 v143, 0x3fb8aa3b, v143
	v_exp_f32_e32 v140, v140
	v_exp_f32_e32 v141, v141
	v_exp_f32_e32 v142, v142
	v_exp_f32_e32 v143, v143
	v_mul_f32_e32 v136, 0.5, v136
	v_mul_f32_e32 v137, 0.5, v137
	v_mul_f32_e32 v138, 0.5, v138
	v_mul_f32_e32 v139, 0.5, v139
	v_add_f32_e32 v140, 1.0, v140
	v_add_f32_e32 v141, 1.0, v141
	v_add_f32_e32 v142, 1.0, v142
	v_add_f32_e32 v143, 1.0, v143
	v_rcp_f32_e32 v140, v140
	v_rcp_f32_e32 v141, v141
	v_rcp_f32_e32 v142, v142
	v_rcp_f32_e32 v143, v143
	v_fmac_f32_e32 v30, v132, v34
	v_fmac_f32_e32 v31, v133, v35
	v_fmac_f32_e32 v32, v134, v36
	v_fmac_f32_e32 v33, v135, v37
	v_fma_f32 v140, v140, -2.0, 1.0
	v_fma_f32 v141, v141, -2.0, 1.0
	v_fma_f32 v142, v142, -2.0, 1.0
	v_fma_f32 v143, v143, -2.0, 1.0
	v_add_f32_e32 v140, 1.0, v140
	v_add_f32_e32 v141, 1.0, v141
	v_add_f32_e32 v142, 1.0, v142
	v_add_f32_e32 v143, 1.0, v143
	v_mul_f32_e32 v136, v136, v140
	v_mul_f32_e32 v137, v137, v141
	v_mul_f32_e32 v138, v138, v142
	v_mul_f32_e32 v139, v139, v143
	v_mul_f32_e32 v136, v30, v136
	v_mul_f32_e32 v137, v31, v137
	v_mul_f32_e32 v138, v32, v138
	v_mul_f32_e32 v139, v33, v139
	v_cvt_pk_bf16_f32 v140, v136, v137
	v_cvt_pk_bf16_f32 v141, v138, v139
	global_store_dwordx2 v130, v[140:141], s[24:25]
	s_add_u32 s24, s24, 0x800
	s_addc_u32 s25, s25, 0
	s_nop 0
	v_lshlrev_b32_e32 v136, 16, v48
	v_and_b32_e32 v137, 0xffff0000, v48
	v_lshlrev_b32_e32 v138, 16, v49
	v_and_b32_e32 v139, 0xffff0000, v49
	v_mul_f32_e32 v140, 0x3d372713, v136
	v_mul_f32_e32 v141, 0x3d372713, v137
	v_mul_f32_e32 v142, 0x3d372713, v138
	v_mul_f32_e32 v143, 0x3d372713, v139
	v_mul_f32_e32 v140, v140, v136
	v_mul_f32_e32 v141, v141, v137
	v_mul_f32_e32 v142, v142, v138
	v_mul_f32_e32 v143, v143, v139
	v_fma_f32 v140, v140, v136, v136
	v_fma_f32 v141, v141, v137, v137
	v_fma_f32 v142, v142, v138, v138
	v_fma_f32 v143, v143, v139, v139
	v_mul_f32_e32 v140, 0x3f4c422a, v140
	v_mul_f32_e32 v141, 0x3f4c422a, v141
	v_mul_f32_e32 v142, 0x3f4c422a, v142
	v_mul_f32_e32 v143, 0x3f4c422a, v143
	v_add_f32_e32 v140, v140, v140
	v_add_f32_e32 v141, v141, v141
	v_add_f32_e32 v142, v142, v142
	v_add_f32_e32 v143, v143, v143
	v_mul_f32_e32 v140, 0x3fb8aa3b, v140
	v_mul_f32_e32 v141, 0x3fb8aa3b, v141
	v_mul_f32_e32 v142, 0x3fb8aa3b, v142
	v_mul_f32_e32 v143, 0x3fb8aa3b, v143
	v_exp_f32_e32 v140, v140
	v_exp_f32_e32 v141, v141
	v_exp_f32_e32 v142, v142
	v_exp_f32_e32 v143, v143
	v_mul_f32_e32 v136, 0.5, v136
	v_mul_f32_e32 v137, 0.5, v137
	v_mul_f32_e32 v138, 0.5, v138
	v_mul_f32_e32 v139, 0.5, v139
	v_add_f32_e32 v140, 1.0, v140
	v_add_f32_e32 v141, 1.0, v141
	v_add_f32_e32 v142, 1.0, v142
	v_add_f32_e32 v143, 1.0, v143
	v_rcp_f32_e32 v140, v140
	v_rcp_f32_e32 v141, v141
	v_rcp_f32_e32 v142, v142
	v_rcp_f32_e32 v143, v143
	v_fmac_f32_e32 v40, v132, v44
	v_fmac_f32_e32 v41, v133, v45
	v_fmac_f32_e32 v42, v134, v46
	v_fmac_f32_e32 v43, v135, v47
	v_fma_f32 v140, v140, -2.0, 1.0
	v_fma_f32 v141, v141, -2.0, 1.0
	v_fma_f32 v142, v142, -2.0, 1.0
	v_fma_f32 v143, v143, -2.0, 1.0
	v_add_f32_e32 v140, 1.0, v140
	v_add_f32_e32 v141, 1.0, v141
	v_add_f32_e32 v142, 1.0, v142
	v_add_f32_e32 v143, 1.0, v143
	v_mul_f32_e32 v136, v136, v140
	v_mul_f32_e32 v137, v137, v141
	v_mul_f32_e32 v138, v138, v142
	v_mul_f32_e32 v139, v139, v143
	v_mul_f32_e32 v136, v40, v136
	v_mul_f32_e32 v137, v41, v137
	v_mul_f32_e32 v138, v42, v138
	v_mul_f32_e32 v139, v43, v139
	v_cvt_pk_bf16_f32 v140, v136, v137
	v_cvt_pk_bf16_f32 v141, v138, v139
	global_store_dwordx2 v130, v[140:141], s[24:25]
	s_add_u32 s24, s24, 0x800
	s_addc_u32 s25, s25, 0
	s_nop 0
	v_lshlrev_b32_e32 v136, 16, v58
; __device__ __forceinline__ float bf2f(u16 h) { return __uint_as_float(((unsigned)h) << 16); }
; __device__ __forceinline__ void lru_fix_phase(const Params& p, const XcdBarrier& xb) {
;     ...
;       for (int q = 0; q < 16; q++) {
;         const int row = r0 + q;
;         float hv = HL[(size_t)row * 512 + ch] + CA[(size_t)row * 512 + ch] * carry;
;         float gate = geluf_(bf2f(Q[(size_t)row * 2048 + 1024 + ch]));
;         Y[(size_t)row * 1024 + 512 + ch] = f2bf(hv * gate);
;         if ((row & 2047) == 2047) p.out[OUT_PLRU + (size_t)(row >> 11) * 512 + ch] = hv;
;       }
;       carry = sg[(size_t)(s0 + u) * 1024] * carry + sg[(size_t)(s0 + u) * 1024 + 512];
;     }
	v_and_b32_e32 v137, 0xffff0000, v58
	v_lshlrev_b32_e32 v138, 16, v59
	v_and_b32_e32 v139, 0xffff0000, v59
	v_mul_f32_e32 v140, 0x3d372713, v136
	v_mul_f32_e32 v141, 0x3d372713, v137
	v_mul_f32_e32 v142, 0x3d372713, v138
	v_mul_f32_e32 v143, 0x3d372713, v139
	v_mul_f32_e32 v140, v140, v136
	v_mul_f32_e32 v141, v141, v137
	v_mul_f32_e32 v142, v142, v138
	v_mul_f32_e32 v143, v143, v139
	v_fma_f32 v140, v140, v136, v136
	v_fma_f32 v141, v141, v137, v137
	v_fma_f32 v142, v142, v138, v138
	v_fma_f32 v143, v143, v139, v139
	v_mul_f32_e32 v140, 0x3f4c422a, v140
	v_mul_f32_e32 v141, 0x3f4c422a, v141
	v_mul_f32_e32 v142, 0x3f4c422a, v142
	v_mul_f32_e32 v143, 0x3f4c422a, v143
	v_add_f32_e32 v140, v140, v140
	v_add_f32_e32 v141, v141, v141
	v_add_f32_e32 v142, v142, v142
	v_add_f32_e32 v143, v143, v143
	v_mul_f32_e32 v140, 0x3fb8aa3b, v140
	v_mul_f32_e32 v141, 0x3fb8aa3b, v141
	v_mul_f32_e32 v142, 0x3fb8aa3b, v142
	v_mul_f32_e32 v143, 0x3fb8aa3b, v143
	v_exp_f32_e32 v140, v140
	v_exp_f32_e32 v141, v141
	v_exp_f32_e32 v142, v142
	v_exp_f32_e32 v143, v143
	v_mul_f32_e32 v136, 0.5, v136
	v_mul_f32_e32 v137, 0.5, v137
	v_mul_f32_e32 v138, 0.5, v138
	v_mul_f32_e32 v139, 0.5, v139
	v_add_f32_e32 v140, 1.0, v140
	v_add_f32_e32 v141, 1.0, v141
	v_add_f32_e32 v142, 1.0, v142
	v_add_f32_e32 v143, 1.0, v143
	v_rcp_f32_e32 v140, v140
	v_rcp_f32_e32 v141, v141
	v_rcp_f32_e32 v142, v142
	v_rcp_f32_e32 v143, v143
	v_fmac_f32_e32 v50, v132, v54
	v_fmac_f32_e32 v51, v133, v55
	v_fmac_f32_e32 v52, v134, v56
	v_fmac_f32_e32 v53, v135, v57
	v_fma_f32 v140, v140, -2.0, 1.0
	v_fma_f32 v141, v141, -2.0, 1.0
	v_fma_f32 v142, v142, -2.0, 1.0
	v_fma_f32 v143, v143, -2.0, 1.0
	v_add_f32_e32 v140, 1.0, v140
	v_add_f32_e32 v141, 1.0, v141
	v_add_f32_e32 v142, 1.0, v142
	v_add_f32_e32 v143, 1.0, v143
	v_mul_f32_e32 v136, v136, v140
	v_mul_f32_e32 v137, v137, v141
	v_mul_f32_e32 v138, v138, v142
	v_mul_f32_e32 v139, v139, v143
	v_mul_f32_e32 v136, v50, v136
	v_mul_f32_e32 v137, v51, v137
	v_mul_f32_e32 v138, v52, v138
	v_mul_f32_e32 v139, v53, v139
	v_cvt_pk_bf16_f32 v140, v136, v137
	v_cvt_pk_bf16_f32 v141, v138, v139
	global_store_dwordx2 v130, v[140:141], s[24:25]
	s_add_u32 s24, s24, 0x800
	s_addc_u32 s25, s25, 0
	s_nop 0
	v_lshlrev_b32_e32 v136, 16, v68
	v_and_b32_e32 v137, 0xffff0000, v68
	v_lshlrev_b32_e32 v138, 16, v69
	v_and_b32_e32 v139, 0xffff0000, v69
	v_mul_f32_e32 v140, 0x3d372713, v136
	v_mul_f32_e32 v141, 0x3d372713, v137
	v_mul_f32_e32 v142, 0x3d372713, v138
	v_mul_f32_e32 v143, 0x3d372713, v139
	v_mul_f32_e32 v140, v140, v136
	v_mul_f32_e32 v141, v141, v137
	v_mul_f32_e32 v142, v142, v138
	v_mul_f32_e32 v143, v143, v139
	v_fma_f32 v140, v140, v136, v136
	v_fma_f32 v141, v141, v137, v137
	v_fma_f32 v142, v142, v138, v138
	v_fma_f32 v143, v143, v139, v139
	v_mul_f32_e32 v140, 0x3f4c422a, v140
	v_mul_f32_e32 v141, 0x3f4c422a, v141
	v_mul_f32_e32 v142, 0x3f4c422a, v142
	v_mul_f32_e32 v143, 0x3f4c422a, v143
	v_add_f32_e32 v140, v140, v140
	v_add_f32_e32 v141, v141, v141
	v_add_f32_e32 v142, v142, v142
	v_add_f32_e32 v143, v143, v143
	v_mul_f32_e32 v140, 0x3fb8aa3b, v140
	v_mul_f32_e32 v141, 0x3fb8aa3b, v141
	v_mul_f32_e32 v142, 0x3fb8aa3b, v142
	v_mul_f32_e32 v143, 0x3fb8aa3b, v143
	v_exp_f32_e32 v140, v140
	v_exp_f32_e32 v141, v141
	v_exp_f32_e32 v142, v142
	v_exp_f32_e32 v143, v143
	v_mul_f32_e32 v136, 0.5, v136
	v_mul_f32_e32 v137, 0.5, v137
	v_mul_f32_e32 v138, 0.5, v138
	v_mul_f32_e32 v139, 0.5, v139
	v_add_f32_e32 v140, 1.0, v140
	v_add_f32_e32 v141, 1.0, v141
	v_add_f32_e32 v142, 1.0, v142
	v_add_f32_e32 v143, 1.0, v143
	v_rcp_f32_e32 v140, v140
	v_rcp_f32_e32 v141, v141
	v_rcp_f32_e32 v142, v142
	v_rcp_f32_e32 v143, v143
	v_fmac_f32_e32 v60, v132, v64
	v_fmac_f32_e32 v61, v133, v65
	v_fmac_f32_e32 v62, v134, v66
	v_fmac_f32_e32 v63, v135, v67
	v_fma_f32 v140, v140, -2.0, 1.0
	v_fma_f32 v141, v141, -2.0, 1.0
	v_fma_f32 v142, v142, -2.0, 1.0
	v_fma_f32 v143, v143, -2.0, 1.0
	v_add_f32_e32 v140, 1.0, v140
	v_add_f32_e32 v141, 1.0, v141
	v_add_f32_e32 v142, 1.0, v142
	v_add_f32_e32 v143, 1.0, v143
	v_mul_f32_e32 v136, v136, v140
	v_mul_f32_e32 v137, v137, v141
	v_mul_f32_e32 v138, v138, v142
	v_mul_f32_e32 v139, v139, v143
	v_mul_f32_e32 v136, v60, v136
	v_mul_f32_e32 v137, v61, v137
	v_mul_f32_e32 v138, v62, v138
	v_mul_f32_e32 v139, v63, v139
	v_cvt_pk_bf16_f32 v140, v136, v137
	v_cvt_pk_bf16_f32 v141, v138, v139
	global_store_dwordx2 v130, v[140:141], s[24:25]
	s_add_u32 s24, s24, 0x800
	s_addc_u32 s25, s25, 0
	s_nop 0
	v_lshlrev_b32_e32 v136, 16, v78
	v_and_b32_e32 v137, 0xffff0000, v78
	v_lshlrev_b32_e32 v138, 16, v79
	v_and_b32_e32 v139, 0xffff0000, v79
	v_mul_f32_e32 v140, 0x3d372713, v136
	v_mul_f32_e32 v141, 0x3d372713, v137
	v_mul_f32_e32 v142, 0x3d372713, v138
	v_mul_f32_e32 v143, 0x3d372713, v139
	v_mul_f32_e32 v140, v140, v136
	v_mul_f32_e32 v141, v141, v137
	v_mul_f32_e32 v142, v142, v138
	v_mul_f32_e32 v143, v143, v139
	v_fma_f32 v140, v140, v136, v136
	v_fma_f32 v141, v141, v137, v137
	v_fma_f32 v142, v142, v138, v138
	v_fma_f32 v143, v143, v139, v139
	v_mul_f32_e32 v140, 0x3f4c422a, v140
	v_mul_f32_e32 v141, 0x3f4c422a, v141
	v_mul_f32_e32 v142, 0x3f4c422a, v142
	v_mul_f32_e32 v143, 0x3f4c422a, v143
	v_add_f32_e32 v140, v140, v140
	v_add_f32_e32 v141, v141, v141
	v_add_f32_e32 v142, v142, v142
	v_add_f32_e32 v143, v143, v143
	v_mul_f32_e32 v140, 0x3fb8aa3b, v140
	v_mul_f32_e32 v141, 0x3fb8aa3b, v141
	v_mul_f32_e32 v142, 0x3fb8aa3b, v142
	v_mul_f32_e32 v143, 0x3fb8aa3b, v143
	v_exp_f32_e32 v140, v140
	v_exp_f32_e32 v141, v141
	v_exp_f32_e32 v142, v142
	v_exp_f32_e32 v143, v143
	v_mul_f32_e32 v136, 0.5, v136
	v_mul_f32_e32 v137, 0.5, v137
	v_mul_f32_e32 v138, 0.5, v138
	v_mul_f32_e32 v139, 0.5, v139
	v_add_f32_e32 v140, 1.0, v140
	v_add_f32_e32 v141, 1.0, v141
	v_add_f32_e32 v142, 1.0, v142
	v_add_f32_e32 v143, 1.0, v143
	v_rcp_f32_e32 v140, v140
	v_rcp_f32_e32 v141, v141
	v_rcp_f32_e32 v142, v142
	v_rcp_f32_e32 v143, v143
	v_fmac_f32_e32 v70, v132, v74
	v_fmac_f32_e32 v71, v133, v75
	v_fmac_f32_e32 v72, v134, v76
	v_fmac_f32_e32 v73, v135, v77
	v_fma_f32 v140, v140, -2.0, 1.0
	v_fma_f32 v141, v141, -2.0, 1.0
	v_fma_f32 v142, v142, -2.0, 1.0
	v_fma_f32 v143, v143, -2.0, 1.0
	v_add_f32_e32 v140, 1.0, v140
	v_add_f32_e32 v141, 1.0, v141
	v_add_f32_e32 v142, 1.0, v142
	v_add_f32_e32 v143, 1.0, v143
	v_mul_f32_e32 v136, v136, v140
	v_mul_f32_e32 v137, v137, v141
	v_mul_f32_e32 v138, v138, v142
	v_mul_f32_e32 v139, v139, v143
	v_mul_f32_e32 v136, v70, v136
	v_mul_f32_e32 v137, v71, v137
	v_mul_f32_e32 v138, v72, v138
	v_mul_f32_e32 v139, v73, v139
	v_cvt_pk_bf16_f32 v140, v136, v137
	v_cvt_pk_bf16_f32 v141, v138, v139
	global_store_dwordx2 v130, v[140:141], s[24:25]
	s_add_u32 s24, s24, 0x800
	s_addc_u32 s25, s25, 0
	s_cmp_lg_u32 s18, 0x7f
	s_cbranch_scc1 .Llf_nolast
	s_lshl_b32 s19, s14, 11
	s_add_u32 s28, s94, 0x43be000
	s_addc_u32 s29, s95, 0
	s_add_u32 s28, s28, s19
	s_addc_u32 s29, s29, 0
	global_store_dwordx4 v129, v[70:73], s[28:29]
.Llf_nolast:
	s_waitcnt vmcnt(0)
.LBB0_1775:
	s_movk_i32 s0, 0x400
